# v94 plus phase-1 transposes-first for half of the blocks plus norm-phase row loads issued before the parameter wait
# baseline (speedup 1.0000x reference)
.Lp1_norm_first:
	s_lshl_b32 s96, s22, 3
	s_lshr_b32 s97, s70, 6
	s_add_u32 s96, s96, s97
	s_lshl_b32 s97, s96, 4
	s_cmpk_ge_u32 s97, 0x8000
	s_cbranch_scc1 .Lnp1_done
	s_load_dwordx2 s[88:89], s[0:1], 0x0
	s_load_dwordx2 s[90:91], s[0:1], 0x18
	s_load_dwordx2 s[92:93], s[0:1], 0x140
	s_load_dwordx2 s[94:95], s[0:1], 0x158
	v_mbcnt_hi_u32_b32 v0, -1, v210
	v_lshlrev_b32_e32 v1, 4, v0
	s_waitcnt lgkmcnt(0)
	s_add_u32 s90, s90, 0
	s_addc_u32 s91, s91, 0
	global_load_dwordx4 v[112:115], v1, s[90:91] nt
	global_load_dwordx4 v[116:119], v1, s[90:91] offset:1024 nt
	global_load_dwordx4 v[120:123], v1, s[90:91] offset:2048 nt
	global_load_dwordx4 v[124:127], v1, s[90:91] offset:3072 nt
	s_lshr_b32 s98, s97, 12
	s_add_u32 s98, s98, 0
	s_mul_i32 s98, s98, 0x3000
	s_add_u32 s92, s92, s98
	s_addc_u32 s93, s93, 0
	global_load_dwordx4 v[144:147], v1, s[92:93] nt
	global_load_dwordx4 v[148:151], v1, s[92:93] offset:1024 nt
	global_load_dwordx4 v[152:155], v1, s[92:93] offset:2048 nt
	global_load_dwordx4 v[156:159], v1, s[92:93] offset:3072 nt
	s_add_u32 s92, s92, 0x1000
	s_addc_u32 s93, s93, 0
	global_load_dwordx4 v[128:131], v1, s[92:93] nt
	global_load_dwordx4 v[132:135], v1, s[92:93] offset:1024 nt
	global_load_dwordx4 v[136:139], v1, s[92:93] offset:2048 nt
	global_load_dwordx4 v[140:143], v1, s[92:93] offset:3072 nt
	s_load_dwordx2 s[90:91], s[0:1], 0x210
	s_load_dwordx2 s[92:93], s[0:1], 0x218
	s_add_u32 s98, s97, 0
	s_lshl_b32 s98, s98, 12
	v_add_u32_e32 v3, s98, v1
	global_load_dwordx4 v[16:19], v3, s[88:89] nt
	global_load_dwordx4 v[20:23], v3, s[88:89] offset:1024 nt
	global_load_dwordx4 v[24:27], v3, s[88:89] offset:2048 nt
	global_load_dwordx4 v[28:31], v3, s[88:89] offset:3072 nt
	s_add_u32 s98, s97, 1
	s_lshl_b32 s98, s98, 12
	v_add_u32_e32 v3, s98, v1
	global_load_dwordx4 v[32:35], v3, s[88:89] nt
	global_load_dwordx4 v[36:39], v3, s[88:89] offset:1024 nt
	global_load_dwordx4 v[40:43], v3, s[88:89] offset:2048 nt
	global_load_dwordx4 v[44:47], v3, s[88:89] offset:3072 nt
	s_add_u32 s98, s97, 2
	s_lshl_b32 s98, s98, 12
	v_add_u32_e32 v3, s98, v1
	global_load_dwordx4 v[48:51], v3, s[88:89] nt
	global_load_dwordx4 v[52:55], v3, s[88:89] offset:1024 nt
	global_load_dwordx4 v[56:59], v3, s[88:89] offset:2048 nt
	global_load_dwordx4 v[60:63], v3, s[88:89] offset:3072 nt
	s_add_u32 s98, s97, 3
	s_lshl_b32 s98, s98, 12
	v_add_u32_e32 v3, s98, v1
	global_load_dwordx4 v[64:67], v3, s[88:89] nt
	global_load_dwordx4 v[68:71], v3, s[88:89] offset:1024 nt
	global_load_dwordx4 v[72:75], v3, s[88:89] offset:2048 nt
	global_load_dwordx4 v[76:79], v3, s[88:89] offset:3072 nt
	s_add_u32 s98, s97, 4
	s_lshl_b32 s98, s98, 12
	v_add_u32_e32 v3, s98, v1
	global_load_dwordx4 v[80:83], v3, s[88:89] nt
	global_load_dwordx4 v[84:87], v3, s[88:89] offset:1024 nt
	global_load_dwordx4 v[88:91], v3, s[88:89] offset:2048 nt
	global_load_dwordx4 v[92:95], v3, s[88:89] offset:3072 nt
	s_waitcnt vmcnt(0) lgkmcnt(0)
	v_pk_add_f32 v[128:129], v[128:129], 1.0 op_sel_hi:[1,0]
	v_pk_add_f32 v[130:131], v[130:131], 1.0 op_sel_hi:[1,0]
	v_pk_add_f32 v[132:133], v[132:133], 1.0 op_sel_hi:[1,0]
	v_pk_add_f32 v[134:135], v[134:135], 1.0 op_sel_hi:[1,0]
	v_pk_add_f32 v[136:137], v[136:137], 1.0 op_sel_hi:[1,0]
	v_pk_add_f32 v[138:139], v[138:139], 1.0 op_sel_hi:[1,0]
	v_pk_add_f32 v[140:141], v[140:141], 1.0 op_sel_hi:[1,0]
	v_pk_add_f32 v[142:143], v[142:143], 1.0 op_sel_hi:[1,0]
	s_add_u32 s98, s97, 5
	s_lshl_b32 s98, s98, 12
	v_add_u32_e32 v3, s98, v1
	global_load_dwordx4 v[96:99], v3, s[88:89] nt
	global_load_dwordx4 v[100:103], v3, s[88:89] offset:1024 nt
	global_load_dwordx4 v[104:107], v3, s[88:89] offset:2048 nt
	global_load_dwordx4 v[108:111], v3, s[88:89] offset:3072 nt
	s_waitcnt vmcnt(20)
	v_mul_f32_e32 v4, v16, v16
	v_fma_f32 v4, v17, v17, v4
	v_fma_f32 v4, v18, v18, v4
	v_fma_f32 v4, v19, v19, v4
	v_fma_f32 v4, v20, v20, v4
	v_fma_f32 v4, v21, v21, v4
	v_fma_f32 v4, v22, v22, v4
	v_fma_f32 v4, v23, v23, v4
	v_fma_f32 v4, v24, v24, v4
	v_fma_f32 v4, v25, v25, v4
	v_fma_f32 v4, v26, v26, v4
	v_fma_f32 v4, v27, v27, v4
	v_fma_f32 v4, v28, v28, v4
	v_fma_f32 v4, v29, v29, v4
	v_fma_f32 v4, v30, v30, v4
	v_fma_f32 v4, v31, v31, v4
	s_nop 1
	v_add_f32_dpp v5, v4, v4 quad_perm:[1,0,3,2] row_mask:0xf bank_mask:0xf
	s_nop 1
	v_add_f32_dpp v4, v5, v5 quad_perm:[2,3,0,1] row_mask:0xf bank_mask:0xf
	s_nop 1
	v_add_f32_dpp v5, v4, v4 row_half_mirror row_mask:0xf bank_mask:0xf
	s_nop 1
	v_add_f32_dpp v4, v5, v5 row_mirror row_mask:0xf bank_mask:0xf
	s_nop 1
	v_readlane_b32 s98, v4, 0
	v_readlane_b32 s99, v4, 16
	s_nop 3
	v_mov_b32_e32 v5, s98
	v_add_f32_e32 v5, s99, v5
	v_readlane_b32 s98, v4, 32
	v_readlane_b32 s99, v4, 48
	s_nop 3
	v_add_f32_e32 v5, s98, v5
	v_add_f32_e32 v5, s99, v5
	v_mul_f32_e32 v5, 0x3a800000, v5
	v_add_f32_e32 v5, 0x358637bd, v5
	v_rsq_f32_e32 v6, v5
	s_nop 0
	s_add_u32 s98, s97, 0
	v_pk_mul_f32 v[16:17], v[16:17], v[6:7] op_sel_hi:[1,0]
	v_pk_mul_f32 v[18:19], v[18:19], v[6:7] op_sel_hi:[1,0]
	v_pk_mul_f32 v[20:21], v[20:21], v[6:7] op_sel_hi:[1,0]
	v_pk_mul_f32 v[22:23], v[22:23], v[6:7] op_sel_hi:[1,0]
	v_pk_mul_f32 v[24:25], v[24:25], v[6:7] op_sel_hi:[1,0]
	v_pk_mul_f32 v[26:27], v[26:27], v[6:7] op_sel_hi:[1,0]
	v_pk_mul_f32 v[28:29], v[28:29], v[6:7] op_sel_hi:[1,0]
	v_pk_mul_f32 v[30:31], v[30:31], v[6:7] op_sel_hi:[1,0]
	v_pk_mul_f32 v[16:17], v[16:17], v[112:113]
	v_pk_mul_f32 v[18:19], v[18:19], v[114:115]
	v_pk_mul_f32 v[20:21], v[20:21], v[116:117]
	v_pk_mul_f32 v[22:23], v[22:23], v[118:119]
	v_pk_mul_f32 v[24:25], v[24:25], v[120:121]
	v_pk_mul_f32 v[26:27], v[26:27], v[122:123]
	v_pk_mul_f32 v[28:29], v[28:29], v[124:125]
	v_pk_mul_f32 v[30:31], v[30:31], v[126:127]
	v_pk_fma_f32 v[16:17], v[16:17], v[128:129], v[144:145]
	v_pk_fma_f32 v[18:19], v[18:19], v[130:131], v[146:147]
	v_pk_fma_f32 v[20:21], v[20:21], v[132:133], v[148:149]
	v_pk_fma_f32 v[22:23], v[22:23], v[134:135], v[150:151]
	v_pk_fma_f32 v[24:25], v[24:25], v[136:137], v[152:153]
	v_pk_fma_f32 v[26:27], v[26:27], v[138:139], v[154:155]
	v_pk_fma_f32 v[28:29], v[28:29], v[140:141], v[156:157]
	v_pk_fma_f32 v[30:31], v[30:31], v[142:143], v[158:159]
	v_cvt_pk_bf16_f32 v16, v16, v17
	v_cvt_pk_bf16_f32 v17, v18, v19
	v_cvt_pk_bf16_f32 v18, v20, v21
	v_cvt_pk_bf16_f32 v19, v22, v23
	v_cvt_pk_bf16_f32 v20, v24, v25
	v_cvt_pk_bf16_f32 v21, v26, v27
	v_cvt_pk_bf16_f32 v22, v28, v29
	v_cvt_pk_bf16_f32 v23, v30, v31
	s_lshl_b32 s99, s98, 11
	v_lshl_add_u32 v8, v0, 3, s99
	global_store_dwordx2 v8, v[16:17], s[94:95]
	global_store_dwordx2 v8, v[18:19], s[94:95] offset:512
	global_store_dwordx2 v8, v[20:21], s[94:95] offset:1024
	global_store_dwordx2 v8, v[22:23], s[94:95] offset:1536
	s_lshl_b32 s99, s98, 2
	v_mov_b32_e32 v9, s99
	v_mov_b32_e32 v10, 0
	v_cmp_eq_u32_e32 vcc, 0, v0
	s_and_saveexec_b64 s[98:99], vcc
	global_store_dword v9, v10, s[90:91]
	global_store_dword v9, v10, s[92:93]
	s_or_b64 exec, exec, s[98:99]
	s_add_u32 s98, s97, 6
	s_lshl_b32 s98, s98, 12
	v_add_u32_e32 v3, s98, v1
	global_load_dwordx4 v[16:19], v3, s[88:89] nt
	global_load_dwordx4 v[20:23], v3, s[88:89] offset:1024 nt
	global_load_dwordx4 v[24:27], v3, s[88:89] offset:2048 nt
	global_load_dwordx4 v[28:31], v3, s[88:89] offset:3072 nt
	s_waitcnt vmcnt(26)
	v_mul_f32_e32 v4, v32, v32
	v_fma_f32 v4, v33, v33, v4
	v_fma_f32 v4, v34, v34, v4
	v_fma_f32 v4, v35, v35, v4
	v_fma_f32 v4, v36, v36, v4
	v_fma_f32 v4, v37, v37, v4
	v_fma_f32 v4, v38, v38, v4
	v_fma_f32 v4, v39, v39, v4
	v_fma_f32 v4, v40, v40, v4
	v_fma_f32 v4, v41, v41, v4
	v_fma_f32 v4, v42, v42, v4
	v_fma_f32 v4, v43, v43, v4
	v_fma_f32 v4, v44, v44, v4
	v_fma_f32 v4, v45, v45, v4
	v_fma_f32 v4, v46, v46, v4
	v_fma_f32 v4, v47, v47, v4
	s_nop 1
	v_add_f32_dpp v5, v4, v4 quad_perm:[1,0,3,2] row_mask:0xf bank_mask:0xf
	s_nop 1
	v_add_f32_dpp v4, v5, v5 quad_perm:[2,3,0,1] row_mask:0xf bank_mask:0xf
	s_nop 1
	v_add_f32_dpp v5, v4, v4 row_half_mirror row_mask:0xf bank_mask:0xf
	s_nop 1
	v_add_f32_dpp v4, v5, v5 row_mirror row_mask:0xf bank_mask:0xf
	s_nop 1
	v_readlane_b32 s98, v4, 0
	v_readlane_b32 s99, v4, 16
	s_nop 3
	v_mov_b32_e32 v5, s98
	v_add_f32_e32 v5, s99, v5
	v_readlane_b32 s98, v4, 32
	v_readlane_b32 s99, v4, 48
	s_nop 3
	v_add_f32_e32 v5, s98, v5
	v_add_f32_e32 v5, s99, v5
	v_mul_f32_e32 v5, 0x3a800000, v5
	v_add_f32_e32 v5, 0x358637bd, v5
	v_rsq_f32_e32 v6, v5
	s_nop 0
	s_add_u32 s98, s97, 1
	v_pk_mul_f32 v[32:33], v[32:33], v[6:7] op_sel_hi:[1,0]
	v_pk_mul_f32 v[34:35], v[34:35], v[6:7] op_sel_hi:[1,0]
	v_pk_mul_f32 v[36:37], v[36:37], v[6:7] op_sel_hi:[1,0]
	v_pk_mul_f32 v[38:39], v[38:39], v[6:7] op_sel_hi:[1,0]
	v_pk_mul_f32 v[40:41], v[40:41], v[6:7] op_sel_hi:[1,0]
	v_pk_mul_f32 v[42:43], v[42:43], v[6:7] op_sel_hi:[1,0]
	v_pk_mul_f32 v[44:45], v[44:45], v[6:7] op_sel_hi:[1,0]
	v_pk_mul_f32 v[46:47], v[46:47], v[6:7] op_sel_hi:[1,0]
	v_pk_mul_f32 v[32:33], v[32:33], v[112:113]
	v_pk_mul_f32 v[34:35], v[34:35], v[114:115]
	v_pk_mul_f32 v[36:37], v[36:37], v[116:117]
	v_pk_mul_f32 v[38:39], v[38:39], v[118:119]
	v_pk_mul_f32 v[40:41], v[40:41], v[120:121]
	v_pk_mul_f32 v[42:43], v[42:43], v[122:123]
	v_pk_mul_f32 v[44:45], v[44:45], v[124:125]
	v_pk_mul_f32 v[46:47], v[46:47], v[126:127]
	v_pk_fma_f32 v[32:33], v[32:33], v[128:129], v[144:145]
	v_pk_fma_f32 v[34:35], v[34:35], v[130:131], v[146:147]
	v_pk_fma_f32 v[36:37], v[36:37], v[132:133], v[148:149]
	v_pk_fma_f32 v[38:39], v[38:39], v[134:135], v[150:151]
	v_pk_fma_f32 v[40:41], v[40:41], v[136:137], v[152:153]
	v_pk_fma_f32 v[42:43], v[42:43], v[138:139], v[154:155]
	v_pk_fma_f32 v[44:45], v[44:45], v[140:141], v[156:157]
	v_pk_fma_f32 v[46:47], v[46:47], v[142:143], v[158:159]
	v_cvt_pk_bf16_f32 v32, v32, v33
	v_cvt_pk_bf16_f32 v33, v34, v35
	v_cvt_pk_bf16_f32 v34, v36, v37
	v_cvt_pk_bf16_f32 v35, v38, v39
	v_cvt_pk_bf16_f32 v36, v40, v41
	v_cvt_pk_bf16_f32 v37, v42, v43
	v_cvt_pk_bf16_f32 v38, v44, v45
	v_cvt_pk_bf16_f32 v39, v46, v47
	s_lshl_b32 s99, s98, 11
	v_lshl_add_u32 v8, v0, 3, s99
	global_store_dwordx2 v8, v[32:33], s[94:95]
	global_store_dwordx2 v8, v[34:35], s[94:95] offset:512
	global_store_dwordx2 v8, v[36:37], s[94:95] offset:1024
	global_store_dwordx2 v8, v[38:39], s[94:95] offset:1536
	s_lshl_b32 s99, s98, 2
	v_mov_b32_e32 v9, s99
	v_mov_b32_e32 v10, 0
	v_cmp_eq_u32_e32 vcc, 0, v0
	s_and_saveexec_b64 s[98:99], vcc
	global_store_dword v9, v10, s[90:91]
	global_store_dword v9, v10, s[92:93]
	s_or_b64 exec, exec, s[98:99]
	s_add_u32 s98, s97, 7
	s_lshl_b32 s98, s98, 12
	v_add_u32_e32 v3, s98, v1
	global_load_dwordx4 v[32:35], v3, s[88:89] nt
	global_load_dwordx4 v[36:39], v3, s[88:89] offset:1024 nt
	global_load_dwordx4 v[40:43], v3, s[88:89] offset:2048 nt
	global_load_dwordx4 v[44:47], v3, s[88:89] offset:3072 nt
	s_waitcnt vmcnt(32)
	v_mul_f32_e32 v4, v48, v48
	v_fma_f32 v4, v49, v49, v4
	v_fma_f32 v4, v50, v50, v4
	v_fma_f32 v4, v51, v51, v4
	v_fma_f32 v4, v52, v52, v4
	v_fma_f32 v4, v53, v53, v4
	v_fma_f32 v4, v54, v54, v4
	v_fma_f32 v4, v55, v55, v4
	v_fma_f32 v4, v56, v56, v4
	v_fma_f32 v4, v57, v57, v4
	v_fma_f32 v4, v58, v58, v4
	v_fma_f32 v4, v59, v59, v4
	v_fma_f32 v4, v60, v60, v4
	v_fma_f32 v4, v61, v61, v4
	v_fma_f32 v4, v62, v62, v4
	v_fma_f32 v4, v63, v63, v4
	s_nop 1
	v_add_f32_dpp v5, v4, v4 quad_perm:[1,0,3,2] row_mask:0xf bank_mask:0xf
	s_nop 1
	v_add_f32_dpp v4, v5, v5 quad_perm:[2,3,0,1] row_mask:0xf bank_mask:0xf
	s_nop 1
	v_add_f32_dpp v5, v4, v4 row_half_mirror row_mask:0xf bank_mask:0xf
	s_nop 1
	v_add_f32_dpp v4, v5, v5 row_mirror row_mask:0xf bank_mask:0xf
	s_nop 1
	v_readlane_b32 s98, v4, 0
	v_readlane_b32 s99, v4, 16
	s_nop 3
	v_mov_b32_e32 v5, s98
	v_add_f32_e32 v5, s99, v5
	v_readlane_b32 s98, v4, 32
	v_readlane_b32 s99, v4, 48
	s_nop 3
	v_add_f32_e32 v5, s98, v5
	v_add_f32_e32 v5, s99, v5
	v_mul_f32_e32 v5, 0x3a800000, v5
	v_add_f32_e32 v5, 0x358637bd, v5
	v_rsq_f32_e32 v6, v5
	s_nop 0
	s_add_u32 s98, s97, 2
	v_pk_mul_f32 v[48:49], v[48:49], v[6:7] op_sel_hi:[1,0]
	v_pk_mul_f32 v[50:51], v[50:51], v[6:7] op_sel_hi:[1,0]
	v_pk_mul_f32 v[52:53], v[52:53], v[6:7] op_sel_hi:[1,0]
	v_pk_mul_f32 v[54:55], v[54:55], v[6:7] op_sel_hi:[1,0]
	v_pk_mul_f32 v[56:57], v[56:57], v[6:7] op_sel_hi:[1,0]
	v_pk_mul_f32 v[58:59], v[58:59], v[6:7] op_sel_hi:[1,0]
	v_pk_mul_f32 v[60:61], v[60:61], v[6:7] op_sel_hi:[1,0]
	v_pk_mul_f32 v[62:63], v[62:63], v[6:7] op_sel_hi:[1,0]
	v_pk_mul_f32 v[48:49], v[48:49], v[112:113]
	v_pk_mul_f32 v[50:51], v[50:51], v[114:115]
	v_pk_mul_f32 v[52:53], v[52:53], v[116:117]
	v_pk_mul_f32 v[54:55], v[54:55], v[118:119]
	v_pk_mul_f32 v[56:57], v[56:57], v[120:121]
	v_pk_mul_f32 v[58:59], v[58:59], v[122:123]
	v_pk_mul_f32 v[60:61], v[60:61], v[124:125]
	v_pk_mul_f32 v[62:63], v[62:63], v[126:127]
	v_pk_fma_f32 v[48:49], v[48:49], v[128:129], v[144:145]
	v_pk_fma_f32 v[50:51], v[50:51], v[130:131], v[146:147]
	v_pk_fma_f32 v[52:53], v[52:53], v[132:133], v[148:149]
	v_pk_fma_f32 v[54:55], v[54:55], v[134:135], v[150:151]
	v_pk_fma_f32 v[56:57], v[56:57], v[136:137], v[152:153]
	v_pk_fma_f32 v[58:59], v[58:59], v[138:139], v[154:155]
	v_pk_fma_f32 v[60:61], v[60:61], v[140:141], v[156:157]
	v_pk_fma_f32 v[62:63], v[62:63], v[142:143], v[158:159]
	v_cvt_pk_bf16_f32 v48, v48, v49
	v_cvt_pk_bf16_f32 v49, v50, v51
	v_cvt_pk_bf16_f32 v50, v52, v53
	v_cvt_pk_bf16_f32 v51, v54, v55
	v_cvt_pk_bf16_f32 v52, v56, v57
	v_cvt_pk_bf16_f32 v53, v58, v59
	v_cvt_pk_bf16_f32 v54, v60, v61
	v_cvt_pk_bf16_f32 v55, v62, v63
	s_lshl_b32 s99, s98, 11
	v_lshl_add_u32 v8, v0, 3, s99
	global_store_dwordx2 v8, v[48:49], s[94:95]
	global_store_dwordx2 v8, v[50:51], s[94:95] offset:512
	global_store_dwordx2 v8, v[52:53], s[94:95] offset:1024
	global_store_dwordx2 v8, v[54:55], s[94:95] offset:1536
	s_lshl_b32 s99, s98, 2
	v_mov_b32_e32 v9, s99
	v_mov_b32_e32 v10, 0
	v_cmp_eq_u32_e32 vcc, 0, v0
	s_and_saveexec_b64 s[98:99], vcc
	global_store_dword v9, v10, s[90:91]
	global_store_dword v9, v10, s[92:93]
	s_or_b64 exec, exec, s[98:99]
	s_add_u32 s98, s97, 8
	s_lshl_b32 s98, s98, 12
	v_add_u32_e32 v3, s98, v1
	global_load_dwordx4 v[48:51], v3, s[88:89] nt
	global_load_dwordx4 v[52:55], v3, s[88:89] offset:1024 nt
	global_load_dwordx4 v[56:59], v3, s[88:89] offset:2048 nt
	global_load_dwordx4 v[60:63], v3, s[88:89] offset:3072 nt
	s_waitcnt vmcnt(38)
	v_mul_f32_e32 v4, v64, v64
	v_fma_f32 v4, v65, v65, v4
	v_fma_f32 v4, v66, v66, v4
	v_fma_f32 v4, v67, v67, v4
	v_fma_f32 v4, v68, v68, v4
	v_fma_f32 v4, v69, v69, v4
	v_fma_f32 v4, v70, v70, v4
	v_fma_f32 v4, v71, v71, v4
	v_fma_f32 v4, v72, v72, v4
	v_fma_f32 v4, v73, v73, v4
	v_fma_f32 v4, v74, v74, v4
	v_fma_f32 v4, v75, v75, v4
	v_fma_f32 v4, v76, v76, v4
	v_fma_f32 v4, v77, v77, v4
	v_fma_f32 v4, v78, v78, v4
	v_fma_f32 v4, v79, v79, v4
	s_nop 1
	v_add_f32_dpp v5, v4, v4 quad_perm:[1,0,3,2] row_mask:0xf bank_mask:0xf
	s_nop 1
	v_add_f32_dpp v4, v5, v5 quad_perm:[2,3,0,1] row_mask:0xf bank_mask:0xf
	s_nop 1
	v_add_f32_dpp v5, v4, v4 row_half_mirror row_mask:0xf bank_mask:0xf
	s_nop 1
	v_add_f32_dpp v4, v5, v5 row_mirror row_mask:0xf bank_mask:0xf
	s_nop 1
	v_readlane_b32 s98, v4, 0
	v_readlane_b32 s99, v4, 16
	s_nop 3
	v_mov_b32_e32 v5, s98
	v_add_f32_e32 v5, s99, v5
	v_readlane_b32 s98, v4, 32
	v_readlane_b32 s99, v4, 48
	s_nop 3
	v_add_f32_e32 v5, s98, v5
	v_add_f32_e32 v5, s99, v5
	v_mul_f32_e32 v5, 0x3a800000, v5
	v_add_f32_e32 v5, 0x358637bd, v5
	v_rsq_f32_e32 v6, v5
	s_nop 0
	s_add_u32 s98, s97, 3
	v_pk_mul_f32 v[64:65], v[64:65], v[6:7] op_sel_hi:[1,0]
	v_pk_mul_f32 v[66:67], v[66:67], v[6:7] op_sel_hi:[1,0]
	v_pk_mul_f32 v[68:69], v[68:69], v[6:7] op_sel_hi:[1,0]
	v_pk_mul_f32 v[70:71], v[70:71], v[6:7] op_sel_hi:[1,0]
	v_pk_mul_f32 v[72:73], v[72:73], v[6:7] op_sel_hi:[1,0]
	v_pk_mul_f32 v[74:75], v[74:75], v[6:7] op_sel_hi:[1,0]
	v_pk_mul_f32 v[76:77], v[76:77], v[6:7] op_sel_hi:[1,0]
	v_pk_mul_f32 v[78:79], v[78:79], v[6:7] op_sel_hi:[1,0]
	v_pk_mul_f32 v[64:65], v[64:65], v[112:113]
	v_pk_mul_f32 v[66:67], v[66:67], v[114:115]
	v_pk_mul_f32 v[68:69], v[68:69], v[116:117]
	v_pk_mul_f32 v[70:71], v[70:71], v[118:119]
	v_pk_mul_f32 v[72:73], v[72:73], v[120:121]
	v_pk_mul_f32 v[74:75], v[74:75], v[122:123]
	v_pk_mul_f32 v[76:77], v[76:77], v[124:125]
	v_pk_mul_f32 v[78:79], v[78:79], v[126:127]
	v_pk_fma_f32 v[64:65], v[64:65], v[128:129], v[144:145]
	v_pk_fma_f32 v[66:67], v[66:67], v[130:131], v[146:147]
	v_pk_fma_f32 v[68:69], v[68:69], v[132:133], v[148:149]
	v_pk_fma_f32 v[70:71], v[70:71], v[134:135], v[150:151]
	v_pk_fma_f32 v[72:73], v[72:73], v[136:137], v[152:153]
	v_pk_fma_f32 v[74:75], v[74:75], v[138:139], v[154:155]
	v_pk_fma_f32 v[76:77], v[76:77], v[140:141], v[156:157]
	v_pk_fma_f32 v[78:79], v[78:79], v[142:143], v[158:159]
	v_cvt_pk_bf16_f32 v64, v64, v65
	v_cvt_pk_bf16_f32 v65, v66, v67
	v_cvt_pk_bf16_f32 v66, v68, v69
	v_cvt_pk_bf16_f32 v67, v70, v71
	v_cvt_pk_bf16_f32 v68, v72, v73
	v_cvt_pk_bf16_f32 v69, v74, v75
	v_cvt_pk_bf16_f32 v70, v76, v77
	v_cvt_pk_bf16_f32 v71, v78, v79
	s_lshl_b32 s99, s98, 11
	v_lshl_add_u32 v8, v0, 3, s99
	global_store_dwordx2 v8, v[64:65], s[94:95]
	global_store_dwordx2 v8, v[66:67], s[94:95] offset:512
	global_store_dwordx2 v8, v[68:69], s[94:95] offset:1024
	global_store_dwordx2 v8, v[70:71], s[94:95] offset:1536
	s_lshl_b32 s99, s98, 2
	v_mov_b32_e32 v9, s99
	v_mov_b32_e32 v10, 0
	v_cmp_eq_u32_e32 vcc, 0, v0
	s_and_saveexec_b64 s[98:99], vcc
	global_store_dword v9, v10, s[90:91]
	global_store_dword v9, v10, s[92:93]
	s_or_b64 exec, exec, s[98:99]
	s_add_u32 s98, s97, 9
	s_lshl_b32 s98, s98, 12
	v_add_u32_e32 v3, s98, v1
	global_load_dwordx4 v[64:67], v3, s[88:89] nt
	global_load_dwordx4 v[68:71], v3, s[88:89] offset:1024 nt
	global_load_dwordx4 v[72:75], v3, s[88:89] offset:2048 nt
	global_load_dwordx4 v[76:79], v3, s[88:89] offset:3072 nt
	s_waitcnt vmcnt(44)
	v_mul_f32_e32 v4, v80, v80
	v_fma_f32 v4, v81, v81, v4
	v_fma_f32 v4, v82, v82, v4
	v_fma_f32 v4, v83, v83, v4
	v_fma_f32 v4, v84, v84, v4
	v_fma_f32 v4, v85, v85, v4
	v_fma_f32 v4, v86, v86, v4
	v_fma_f32 v4, v87, v87, v4
	v_fma_f32 v4, v88, v88, v4
	v_fma_f32 v4, v89, v89, v4
	v_fma_f32 v4, v90, v90, v4
	v_fma_f32 v4, v91, v91, v4
	v_fma_f32 v4, v92, v92, v4
	v_fma_f32 v4, v93, v93, v4
	v_fma_f32 v4, v94, v94, v4
	v_fma_f32 v4, v95, v95, v4
	s_nop 1
	v_add_f32_dpp v5, v4, v4 quad_perm:[1,0,3,2] row_mask:0xf bank_mask:0xf
	s_nop 1
	v_add_f32_dpp v4, v5, v5 quad_perm:[2,3,0,1] row_mask:0xf bank_mask:0xf
	s_nop 1
	v_add_f32_dpp v5, v4, v4 row_half_mirror row_mask:0xf bank_mask:0xf
	s_nop 1
	v_add_f32_dpp v4, v5, v5 row_mirror row_mask:0xf bank_mask:0xf
	s_nop 1
	v_readlane_b32 s98, v4, 0
	v_readlane_b32 s99, v4, 16
	s_nop 3
	v_mov_b32_e32 v5, s98
	v_add_f32_e32 v5, s99, v5
	v_readlane_b32 s98, v4, 32
	v_readlane_b32 s99, v4, 48
	s_nop 3
	v_add_f32_e32 v5, s98, v5
	v_add_f32_e32 v5, s99, v5
	v_mul_f32_e32 v5, 0x3a800000, v5
	v_add_f32_e32 v5, 0x358637bd, v5
	v_rsq_f32_e32 v6, v5
	s_nop 0
	s_add_u32 s98, s97, 4
	v_pk_mul_f32 v[80:81], v[80:81], v[6:7] op_sel_hi:[1,0]
	v_pk_mul_f32 v[82:83], v[82:83], v[6:7] op_sel_hi:[1,0]
	v_pk_mul_f32 v[84:85], v[84:85], v[6:7] op_sel_hi:[1,0]
	v_pk_mul_f32 v[86:87], v[86:87], v[6:7] op_sel_hi:[1,0]
	v_pk_mul_f32 v[88:89], v[88:89], v[6:7] op_sel_hi:[1,0]
	v_pk_mul_f32 v[90:91], v[90:91], v[6:7] op_sel_hi:[1,0]
	v_pk_mul_f32 v[92:93], v[92:93], v[6:7] op_sel_hi:[1,0]
	v_pk_mul_f32 v[94:95], v[94:95], v[6:7] op_sel_hi:[1,0]
	v_pk_mul_f32 v[80:81], v[80:81], v[112:113]
	v_pk_mul_f32 v[82:83], v[82:83], v[114:115]
	v_pk_mul_f32 v[84:85], v[84:85], v[116:117]
	v_pk_mul_f32 v[86:87], v[86:87], v[118:119]
	v_pk_mul_f32 v[88:89], v[88:89], v[120:121]
	v_pk_mul_f32 v[90:91], v[90:91], v[122:123]
	v_pk_mul_f32 v[92:93], v[92:93], v[124:125]
	v_pk_mul_f32 v[94:95], v[94:95], v[126:127]
	v_pk_fma_f32 v[80:81], v[80:81], v[128:129], v[144:145]
	v_pk_fma_f32 v[82:83], v[82:83], v[130:131], v[146:147]
	v_pk_fma_f32 v[84:85], v[84:85], v[132:133], v[148:149]
	v_pk_fma_f32 v[86:87], v[86:87], v[134:135], v[150:151]
	v_pk_fma_f32 v[88:89], v[88:89], v[136:137], v[152:153]
	v_pk_fma_f32 v[90:91], v[90:91], v[138:139], v[154:155]
	v_pk_fma_f32 v[92:93], v[92:93], v[140:141], v[156:157]
	v_pk_fma_f32 v[94:95], v[94:95], v[142:143], v[158:159]
	v_cvt_pk_bf16_f32 v80, v80, v81
	v_cvt_pk_bf16_f32 v81, v82, v83
	v_cvt_pk_bf16_f32 v82, v84, v85
	v_cvt_pk_bf16_f32 v83, v86, v87
	v_cvt_pk_bf16_f32 v84, v88, v89
	v_cvt_pk_bf16_f32 v85, v90, v91
	v_cvt_pk_bf16_f32 v86, v92, v93
	v_cvt_pk_bf16_f32 v87, v94, v95
	s_lshl_b32 s99, s98, 11
	v_lshl_add_u32 v8, v0, 3, s99
	global_store_dwordx2 v8, v[80:81], s[94:95]
	global_store_dwordx2 v8, v[82:83], s[94:95] offset:512
	global_store_dwordx2 v8, v[84:85], s[94:95] offset:1024
	global_store_dwordx2 v8, v[86:87], s[94:95] offset:1536
	s_lshl_b32 s99, s98, 2
	v_mov_b32_e32 v9, s99
	v_mov_b32_e32 v10, 0
	v_cmp_eq_u32_e32 vcc, 0, v0
	s_and_saveexec_b64 s[98:99], vcc
	global_store_dword v9, v10, s[90:91]
	global_store_dword v9, v10, s[92:93]
	s_or_b64 exec, exec, s[98:99]
	s_add_u32 s98, s97, 10
	s_lshl_b32 s98, s98, 12
	v_add_u32_e32 v3, s98, v1
	global_load_dwordx4 v[80:83], v3, s[88:89] nt
	global_load_dwordx4 v[84:87], v3, s[88:89] offset:1024 nt
	global_load_dwordx4 v[88:91], v3, s[88:89] offset:2048 nt
	global_load_dwordx4 v[92:95], v3, s[88:89] offset:3072 nt
	s_waitcnt vmcnt(50)
	v_mul_f32_e32 v4, v96, v96
	v_fma_f32 v4, v97, v97, v4
	v_fma_f32 v4, v98, v98, v4
	v_fma_f32 v4, v99, v99, v4
	v_fma_f32 v4, v100, v100, v4
	v_fma_f32 v4, v101, v101, v4
	v_fma_f32 v4, v102, v102, v4
	v_fma_f32 v4, v103, v103, v4
	v_fma_f32 v4, v104, v104, v4
	v_fma_f32 v4, v105, v105, v4
	v_fma_f32 v4, v106, v106, v4
	v_fma_f32 v4, v107, v107, v4
	v_fma_f32 v4, v108, v108, v4
	v_fma_f32 v4, v109, v109, v4
	v_fma_f32 v4, v110, v110, v4
	v_fma_f32 v4, v111, v111, v4
	s_nop 1
	v_add_f32_dpp v5, v4, v4 quad_perm:[1,0,3,2] row_mask:0xf bank_mask:0xf
	s_nop 1
	v_add_f32_dpp v4, v5, v5 quad_perm:[2,3,0,1] row_mask:0xf bank_mask:0xf
	s_nop 1
	v_add_f32_dpp v5, v4, v4 row_half_mirror row_mask:0xf bank_mask:0xf
	s_nop 1
	v_add_f32_dpp v4, v5, v5 row_mirror row_mask:0xf bank_mask:0xf
	s_nop 1
	v_readlane_b32 s98, v4, 0
	v_readlane_b32 s99, v4, 16
	s_nop 3
	v_mov_b32_e32 v5, s98
	v_add_f32_e32 v5, s99, v5
	v_readlane_b32 s98, v4, 32
	v_readlane_b32 s99, v4, 48
	s_nop 3
	v_add_f32_e32 v5, s98, v5
	v_add_f32_e32 v5, s99, v5
	v_mul_f32_e32 v5, 0x3a800000, v5
	v_add_f32_e32 v5, 0x358637bd, v5
	v_rsq_f32_e32 v6, v5
	s_nop 0
	s_add_u32 s98, s97, 5
	v_pk_mul_f32 v[96:97], v[96:97], v[6:7] op_sel_hi:[1,0]
	v_pk_mul_f32 v[98:99], v[98:99], v[6:7] op_sel_hi:[1,0]
	v_pk_mul_f32 v[100:101], v[100:101], v[6:7] op_sel_hi:[1,0]
	v_pk_mul_f32 v[102:103], v[102:103], v[6:7] op_sel_hi:[1,0]
	v_pk_mul_f32 v[104:105], v[104:105], v[6:7] op_sel_hi:[1,0]
	v_pk_mul_f32 v[106:107], v[106:107], v[6:7] op_sel_hi:[1,0]
	v_pk_mul_f32 v[108:109], v[108:109], v[6:7] op_sel_hi:[1,0]
	v_pk_mul_f32 v[110:111], v[110:111], v[6:7] op_sel_hi:[1,0]
	v_pk_mul_f32 v[96:97], v[96:97], v[112:113]
	v_pk_mul_f32 v[98:99], v[98:99], v[114:115]
	v_pk_mul_f32 v[100:101], v[100:101], v[116:117]
	v_pk_mul_f32 v[102:103], v[102:103], v[118:119]
	v_pk_mul_f32 v[104:105], v[104:105], v[120:121]
	v_pk_mul_f32 v[106:107], v[106:107], v[122:123]
	v_pk_mul_f32 v[108:109], v[108:109], v[124:125]
	v_pk_mul_f32 v[110:111], v[110:111], v[126:127]
	v_pk_fma_f32 v[96:97], v[96:97], v[128:129], v[144:145]
	v_pk_fma_f32 v[98:99], v[98:99], v[130:131], v[146:147]
	v_pk_fma_f32 v[100:101], v[100:101], v[132:133], v[148:149]
	v_pk_fma_f32 v[102:103], v[102:103], v[134:135], v[150:151]
	v_pk_fma_f32 v[104:105], v[104:105], v[136:137], v[152:153]
	v_pk_fma_f32 v[106:107], v[106:107], v[138:139], v[154:155]
	v_pk_fma_f32 v[108:109], v[108:109], v[140:141], v[156:157]
	v_pk_fma_f32 v[110:111], v[110:111], v[142:143], v[158:159]
	v_cvt_pk_bf16_f32 v96, v96, v97
	v_cvt_pk_bf16_f32 v97, v98, v99
	v_cvt_pk_bf16_f32 v98, v100, v101
	v_cvt_pk_bf16_f32 v99, v102, v103
	v_cvt_pk_bf16_f32 v100, v104, v105
	v_cvt_pk_bf16_f32 v101, v106, v107
	v_cvt_pk_bf16_f32 v102, v108, v109
	v_cvt_pk_bf16_f32 v103, v110, v111
	s_lshl_b32 s99, s98, 11
	v_lshl_add_u32 v8, v0, 3, s99
	global_store_dwordx2 v8, v[96:97], s[94:95]
	global_store_dwordx2 v8, v[98:99], s[94:95] offset:512
	global_store_dwordx2 v8, v[100:101], s[94:95] offset:1024
	global_store_dwordx2 v8, v[102:103], s[94:95] offset:1536
	s_lshl_b32 s99, s98, 2
	v_mov_b32_e32 v9, s99
	v_mov_b32_e32 v10, 0
	v_cmp_eq_u32_e32 vcc, 0, v0
	s_and_saveexec_b64 s[98:99], vcc
	global_store_dword v9, v10, s[90:91]
	global_store_dword v9, v10, s[92:93]
	s_or_b64 exec, exec, s[98:99]
	s_add_u32 s98, s97, 11
	s_lshl_b32 s98, s98, 12
	v_add_u32_e32 v3, s98, v1
	global_load_dwordx4 v[96:99], v3, s[88:89] nt
	global_load_dwordx4 v[100:103], v3, s[88:89] offset:1024 nt
	global_load_dwordx4 v[104:107], v3, s[88:89] offset:2048 nt
	global_load_dwordx4 v[108:111], v3, s[88:89] offset:3072 nt
	s_waitcnt vmcnt(50)
	v_mul_f32_e32 v4, v16, v16
	v_fma_f32 v4, v17, v17, v4
	v_fma_f32 v4, v18, v18, v4
	v_fma_f32 v4, v19, v19, v4
	v_fma_f32 v4, v20, v20, v4
	v_fma_f32 v4, v21, v21, v4
	v_fma_f32 v4, v22, v22, v4
	v_fma_f32 v4, v23, v23, v4
	v_fma_f32 v4, v24, v24, v4
	v_fma_f32 v4, v25, v25, v4
	v_fma_f32 v4, v26, v26, v4
	v_fma_f32 v4, v27, v27, v4
	v_fma_f32 v4, v28, v28, v4
	v_fma_f32 v4, v29, v29, v4
	v_fma_f32 v4, v30, v30, v4
	v_fma_f32 v4, v31, v31, v4
	s_nop 1
	v_add_f32_dpp v5, v4, v4 quad_perm:[1,0,3,2] row_mask:0xf bank_mask:0xf
	s_nop 1
	v_add_f32_dpp v4, v5, v5 quad_perm:[2,3,0,1] row_mask:0xf bank_mask:0xf
	s_nop 1
	v_add_f32_dpp v5, v4, v4 row_half_mirror row_mask:0xf bank_mask:0xf
	s_nop 1
	v_add_f32_dpp v4, v5, v5 row_mirror row_mask:0xf bank_mask:0xf
	s_nop 1
	v_readlane_b32 s98, v4, 0
	v_readlane_b32 s99, v4, 16
	s_nop 3
	v_mov_b32_e32 v5, s98
	v_add_f32_e32 v5, s99, v5
	v_readlane_b32 s98, v4, 32
	v_readlane_b32 s99, v4, 48
	s_nop 3
	v_add_f32_e32 v5, s98, v5
	v_add_f32_e32 v5, s99, v5
	v_mul_f32_e32 v5, 0x3a800000, v5
	v_add_f32_e32 v5, 0x358637bd, v5
	v_rsq_f32_e32 v6, v5
	s_nop 0
	s_add_u32 s98, s97, 6
	v_pk_mul_f32 v[16:17], v[16:17], v[6:7] op_sel_hi:[1,0]
	v_pk_mul_f32 v[18:19], v[18:19], v[6:7] op_sel_hi:[1,0]
	v_pk_mul_f32 v[20:21], v[20:21], v[6:7] op_sel_hi:[1,0]
	v_pk_mul_f32 v[22:23], v[22:23], v[6:7] op_sel_hi:[1,0]
	v_pk_mul_f32 v[24:25], v[24:25], v[6:7] op_sel_hi:[1,0]
	v_pk_mul_f32 v[26:27], v[26:27], v[6:7] op_sel_hi:[1,0]
	v_pk_mul_f32 v[28:29], v[28:29], v[6:7] op_sel_hi:[1,0]
	v_pk_mul_f32 v[30:31], v[30:31], v[6:7] op_sel_hi:[1,0]
	v_pk_mul_f32 v[16:17], v[16:17], v[112:113]
	v_pk_mul_f32 v[18:19], v[18:19], v[114:115]
	v_pk_mul_f32 v[20:21], v[20:21], v[116:117]
	v_pk_mul_f32 v[22:23], v[22:23], v[118:119]
	v_pk_mul_f32 v[24:25], v[24:25], v[120:121]
	v_pk_mul_f32 v[26:27], v[26:27], v[122:123]
	v_pk_mul_f32 v[28:29], v[28:29], v[124:125]
	v_pk_mul_f32 v[30:31], v[30:31], v[126:127]
	v_pk_fma_f32 v[16:17], v[16:17], v[128:129], v[144:145]
	v_pk_fma_f32 v[18:19], v[18:19], v[130:131], v[146:147]
	v_pk_fma_f32 v[20:21], v[20:21], v[132:133], v[148:149]
	v_pk_fma_f32 v[22:23], v[22:23], v[134:135], v[150:151]
	v_pk_fma_f32 v[24:25], v[24:25], v[136:137], v[152:153]
	v_pk_fma_f32 v[26:27], v[26:27], v[138:139], v[154:155]
	v_pk_fma_f32 v[28:29], v[28:29], v[140:141], v[156:157]
	v_pk_fma_f32 v[30:31], v[30:31], v[142:143], v[158:159]
	v_cvt_pk_bf16_f32 v16, v16, v17
	v_cvt_pk_bf16_f32 v17, v18, v19
	v_cvt_pk_bf16_f32 v18, v20, v21
	v_cvt_pk_bf16_f32 v19, v22, v23
	v_cvt_pk_bf16_f32 v20, v24, v25
	v_cvt_pk_bf16_f32 v21, v26, v27
	v_cvt_pk_bf16_f32 v22, v28, v29
	v_cvt_pk_bf16_f32 v23, v30, v31
	s_lshl_b32 s99, s98, 11
	v_lshl_add_u32 v8, v0, 3, s99
	global_store_dwordx2 v8, v[16:17], s[94:95]
	global_store_dwordx2 v8, v[18:19], s[94:95] offset:512
	global_store_dwordx2 v8, v[20:21], s[94:95] offset:1024
	global_store_dwordx2 v8, v[22:23], s[94:95] offset:1536
	s_lshl_b32 s99, s98, 2
	v_mov_b32_e32 v9, s99
	v_mov_b32_e32 v10, 0
	v_cmp_eq_u32_e32 vcc, 0, v0
	s_and_saveexec_b64 s[98:99], vcc
	global_store_dword v9, v10, s[90:91]
	global_store_dword v9, v10, s[92:93]
	s_or_b64 exec, exec, s[98:99]
	s_add_u32 s98, s97, 12
	s_lshl_b32 s98, s98, 12
	v_add_u32_e32 v3, s98, v1
	global_load_dwordx4 v[16:19], v3, s[88:89] nt
	global_load_dwordx4 v[20:23], v3, s[88:89] offset:1024 nt
	global_load_dwordx4 v[24:27], v3, s[88:89] offset:2048 nt
	global_load_dwordx4 v[28:31], v3, s[88:89] offset:3072 nt
	s_waitcnt vmcnt(50)
	v_mul_f32_e32 v4, v32, v32
	v_fma_f32 v4, v33, v33, v4
	v_fma_f32 v4, v34, v34, v4
	v_fma_f32 v4, v35, v35, v4
	v_fma_f32 v4, v36, v36, v4
	v_fma_f32 v4, v37, v37, v4
	v_fma_f32 v4, v38, v38, v4
	v_fma_f32 v4, v39, v39, v4
	v_fma_f32 v4, v40, v40, v4
	v_fma_f32 v4, v41, v41, v4
	v_fma_f32 v4, v42, v42, v4
	v_fma_f32 v4, v43, v43, v4
	v_fma_f32 v4, v44, v44, v4
	v_fma_f32 v4, v45, v45, v4
	v_fma_f32 v4, v46, v46, v4
	v_fma_f32 v4, v47, v47, v4
	s_nop 1
	v_add_f32_dpp v5, v4, v4 quad_perm:[1,0,3,2] row_mask:0xf bank_mask:0xf
	s_nop 1
	v_add_f32_dpp v4, v5, v5 quad_perm:[2,3,0,1] row_mask:0xf bank_mask:0xf
	s_nop 1
	v_add_f32_dpp v5, v4, v4 row_half_mirror row_mask:0xf bank_mask:0xf
	s_nop 1
	v_add_f32_dpp v4, v5, v5 row_mirror row_mask:0xf bank_mask:0xf
	s_nop 1
	v_readlane_b32 s98, v4, 0
	v_readlane_b32 s99, v4, 16
	s_nop 3
	v_mov_b32_e32 v5, s98
	v_add_f32_e32 v5, s99, v5
	v_readlane_b32 s98, v4, 32
	v_readlane_b32 s99, v4, 48
	s_nop 3
	v_add_f32_e32 v5, s98, v5
	v_add_f32_e32 v5, s99, v5
	v_mul_f32_e32 v5, 0x3a800000, v5
	v_add_f32_e32 v5, 0x358637bd, v5
	v_rsq_f32_e32 v6, v5
	s_nop 0
	s_add_u32 s98, s97, 7
	v_pk_mul_f32 v[32:33], v[32:33], v[6:7] op_sel_hi:[1,0]
	v_pk_mul_f32 v[34:35], v[34:35], v[6:7] op_sel_hi:[1,0]
	v_pk_mul_f32 v[36:37], v[36:37], v[6:7] op_sel_hi:[1,0]
	v_pk_mul_f32 v[38:39], v[38:39], v[6:7] op_sel_hi:[1,0]
	v_pk_mul_f32 v[40:41], v[40:41], v[6:7] op_sel_hi:[1,0]
	v_pk_mul_f32 v[42:43], v[42:43], v[6:7] op_sel_hi:[1,0]
	v_pk_mul_f32 v[44:45], v[44:45], v[6:7] op_sel_hi:[1,0]
	v_pk_mul_f32 v[46:47], v[46:47], v[6:7] op_sel_hi:[1,0]
	v_pk_mul_f32 v[32:33], v[32:33], v[112:113]
	v_pk_mul_f32 v[34:35], v[34:35], v[114:115]
	v_pk_mul_f32 v[36:37], v[36:37], v[116:117]
	v_pk_mul_f32 v[38:39], v[38:39], v[118:119]
	v_pk_mul_f32 v[40:41], v[40:41], v[120:121]
	v_pk_mul_f32 v[42:43], v[42:43], v[122:123]
	v_pk_mul_f32 v[44:45], v[44:45], v[124:125]
	v_pk_mul_f32 v[46:47], v[46:47], v[126:127]
	v_pk_fma_f32 v[32:33], v[32:33], v[128:129], v[144:145]
	v_pk_fma_f32 v[34:35], v[34:35], v[130:131], v[146:147]
	v_pk_fma_f32 v[36:37], v[36:37], v[132:133], v[148:149]
	v_pk_fma_f32 v[38:39], v[38:39], v[134:135], v[150:151]
	v_pk_fma_f32 v[40:41], v[40:41], v[136:137], v[152:153]
	v_pk_fma_f32 v[42:43], v[42:43], v[138:139], v[154:155]
	v_pk_fma_f32 v[44:45], v[44:45], v[140:141], v[156:157]
	v_pk_fma_f32 v[46:47], v[46:47], v[142:143], v[158:159]
	v_cvt_pk_bf16_f32 v32, v32, v33
	v_cvt_pk_bf16_f32 v33, v34, v35
	v_cvt_pk_bf16_f32 v34, v36, v37
	v_cvt_pk_bf16_f32 v35, v38, v39
	v_cvt_pk_bf16_f32 v36, v40, v41
	v_cvt_pk_bf16_f32 v37, v42, v43
	v_cvt_pk_bf16_f32 v38, v44, v45
	v_cvt_pk_bf16_f32 v39, v46, v47
	s_lshl_b32 s99, s98, 11
	v_lshl_add_u32 v8, v0, 3, s99
	global_store_dwordx2 v8, v[32:33], s[94:95]
	global_store_dwordx2 v8, v[34:35], s[94:95] offset:512
	global_store_dwordx2 v8, v[36:37], s[94:95] offset:1024
	global_store_dwordx2 v8, v[38:39], s[94:95] offset:1536
	s_lshl_b32 s99, s98, 2
	v_mov_b32_e32 v9, s99
	v_mov_b32_e32 v10, 0
	v_cmp_eq_u32_e32 vcc, 0, v0
	s_and_saveexec_b64 s[98:99], vcc
	global_store_dword v9, v10, s[90:91]
	global_store_dword v9, v10, s[92:93]
	s_or_b64 exec, exec, s[98:99]
	s_add_u32 s98, s97, 13
	s_lshl_b32 s98, s98, 12
	v_add_u32_e32 v3, s98, v1
	global_load_dwordx4 v[32:35], v3, s[88:89] nt
	global_load_dwordx4 v[36:39], v3, s[88:89] offset:1024 nt
	global_load_dwordx4 v[40:43], v3, s[88:89] offset:2048 nt
	global_load_dwordx4 v[44:47], v3, s[88:89] offset:3072 nt
	s_waitcnt vmcnt(50)
	v_mul_f32_e32 v4, v48, v48
	v_fma_f32 v4, v49, v49, v4
	v_fma_f32 v4, v50, v50, v4
	v_fma_f32 v4, v51, v51, v4
	v_fma_f32 v4, v52, v52, v4
	v_fma_f32 v4, v53, v53, v4
	v_fma_f32 v4, v54, v54, v4
	v_fma_f32 v4, v55, v55, v4
	v_fma_f32 v4, v56, v56, v4
	v_fma_f32 v4, v57, v57, v4
	v_fma_f32 v4, v58, v58, v4
	v_fma_f32 v4, v59, v59, v4
	v_fma_f32 v4, v60, v60, v4
	v_fma_f32 v4, v61, v61, v4
	v_fma_f32 v4, v62, v62, v4
	v_fma_f32 v4, v63, v63, v4
	s_nop 1
	v_add_f32_dpp v5, v4, v4 quad_perm:[1,0,3,2] row_mask:0xf bank_mask:0xf
	s_nop 1
	v_add_f32_dpp v4, v5, v5 quad_perm:[2,3,0,1] row_mask:0xf bank_mask:0xf
	s_nop 1
	v_add_f32_dpp v5, v4, v4 row_half_mirror row_mask:0xf bank_mask:0xf
	s_nop 1
	v_add_f32_dpp v4, v5, v5 row_mirror row_mask:0xf bank_mask:0xf
	s_nop 1
	v_readlane_b32 s98, v4, 0
	v_readlane_b32 s99, v4, 16
	s_nop 3
	v_mov_b32_e32 v5, s98
	v_add_f32_e32 v5, s99, v5
	v_readlane_b32 s98, v4, 32
	v_readlane_b32 s99, v4, 48
	s_nop 3
	v_add_f32_e32 v5, s98, v5
	v_add_f32_e32 v5, s99, v5
	v_mul_f32_e32 v5, 0x3a800000, v5
	v_add_f32_e32 v5, 0x358637bd, v5
	v_rsq_f32_e32 v6, v5
	s_nop 0
	s_add_u32 s98, s97, 8
	v_pk_mul_f32 v[48:49], v[48:49], v[6:7] op_sel_hi:[1,0]
	v_pk_mul_f32 v[50:51], v[50:51], v[6:7] op_sel_hi:[1,0]
	v_pk_mul_f32 v[52:53], v[52:53], v[6:7] op_sel_hi:[1,0]
	v_pk_mul_f32 v[54:55], v[54:55], v[6:7] op_sel_hi:[1,0]
	v_pk_mul_f32 v[56:57], v[56:57], v[6:7] op_sel_hi:[1,0]
	v_pk_mul_f32 v[58:59], v[58:59], v[6:7] op_sel_hi:[1,0]
	v_pk_mul_f32 v[60:61], v[60:61], v[6:7] op_sel_hi:[1,0]
	v_pk_mul_f32 v[62:63], v[62:63], v[6:7] op_sel_hi:[1,0]
	v_pk_mul_f32 v[48:49], v[48:49], v[112:113]
	v_pk_mul_f32 v[50:51], v[50:51], v[114:115]
	v_pk_mul_f32 v[52:53], v[52:53], v[116:117]
	v_pk_mul_f32 v[54:55], v[54:55], v[118:119]
	v_pk_mul_f32 v[56:57], v[56:57], v[120:121]
	v_pk_mul_f32 v[58:59], v[58:59], v[122:123]
	v_pk_mul_f32 v[60:61], v[60:61], v[124:125]
	v_pk_mul_f32 v[62:63], v[62:63], v[126:127]
	v_pk_fma_f32 v[48:49], v[48:49], v[128:129], v[144:145]
	v_pk_fma_f32 v[50:51], v[50:51], v[130:131], v[146:147]
	v_pk_fma_f32 v[52:53], v[52:53], v[132:133], v[148:149]
	v_pk_fma_f32 v[54:55], v[54:55], v[134:135], v[150:151]
	v_pk_fma_f32 v[56:57], v[56:57], v[136:137], v[152:153]
	v_pk_fma_f32 v[58:59], v[58:59], v[138:139], v[154:155]
	v_pk_fma_f32 v[60:61], v[60:61], v[140:141], v[156:157]
	v_pk_fma_f32 v[62:63], v[62:63], v[142:143], v[158:159]
	v_cvt_pk_bf16_f32 v48, v48, v49
	v_cvt_pk_bf16_f32 v49, v50, v51
	v_cvt_pk_bf16_f32 v50, v52, v53
	v_cvt_pk_bf16_f32 v51, v54, v55
	v_cvt_pk_bf16_f32 v52, v56, v57
	v_cvt_pk_bf16_f32 v53, v58, v59
	v_cvt_pk_bf16_f32 v54, v60, v61
	v_cvt_pk_bf16_f32 v55, v62, v63
	s_lshl_b32 s99, s98, 11
	v_lshl_add_u32 v8, v0, 3, s99
	global_store_dwordx2 v8, v[48:49], s[94:95]
	global_store_dwordx2 v8, v[50:51], s[94:95] offset:512
	global_store_dwordx2 v8, v[52:53], s[94:95] offset:1024
	global_store_dwordx2 v8, v[54:55], s[94:95] offset:1536
	s_lshl_b32 s99, s98, 2
	v_mov_b32_e32 v9, s99
	v_mov_b32_e32 v10, 0
	v_cmp_eq_u32_e32 vcc, 0, v0
	s_and_saveexec_b64 s[98:99], vcc
	global_store_dword v9, v10, s[90:91]
	global_store_dword v9, v10, s[92:93]
	s_or_b64 exec, exec, s[98:99]
	s_add_u32 s98, s97, 14
	s_lshl_b32 s98, s98, 12
	v_add_u32_e32 v3, s98, v1
	global_load_dwordx4 v[48:51], v3, s[88:89] nt
	global_load_dwordx4 v[52:55], v3, s[88:89] offset:1024 nt
	global_load_dwordx4 v[56:59], v3, s[88:89] offset:2048 nt
	global_load_dwordx4 v[60:63], v3, s[88:89] offset:3072 nt
	s_waitcnt vmcnt(50)
	v_mul_f32_e32 v4, v64, v64
	v_fma_f32 v4, v65, v65, v4
	v_fma_f32 v4, v66, v66, v4
	v_fma_f32 v4, v67, v67, v4
	v_fma_f32 v4, v68, v68, v4
	v_fma_f32 v4, v69, v69, v4
	v_fma_f32 v4, v70, v70, v4
	v_fma_f32 v4, v71, v71, v4
	v_fma_f32 v4, v72, v72, v4
	v_fma_f32 v4, v73, v73, v4
	v_fma_f32 v4, v74, v74, v4
	v_fma_f32 v4, v75, v75, v4
	v_fma_f32 v4, v76, v76, v4
	v_fma_f32 v4, v77, v77, v4
	v_fma_f32 v4, v78, v78, v4
	v_fma_f32 v4, v79, v79, v4
	s_nop 1
	v_add_f32_dpp v5, v4, v4 quad_perm:[1,0,3,2] row_mask:0xf bank_mask:0xf
	s_nop 1
	v_add_f32_dpp v4, v5, v5 quad_perm:[2,3,0,1] row_mask:0xf bank_mask:0xf
	s_nop 1
	v_add_f32_dpp v5, v4, v4 row_half_mirror row_mask:0xf bank_mask:0xf
	s_nop 1
	v_add_f32_dpp v4, v5, v5 row_mirror row_mask:0xf bank_mask:0xf
	s_nop 1
	v_readlane_b32 s98, v4, 0
	v_readlane_b32 s99, v4, 16
	s_nop 3
	v_mov_b32_e32 v5, s98
	v_add_f32_e32 v5, s99, v5
	v_readlane_b32 s98, v4, 32
	v_readlane_b32 s99, v4, 48
	s_nop 3
	v_add_f32_e32 v5, s98, v5
	v_add_f32_e32 v5, s99, v5
	v_mul_f32_e32 v5, 0x3a800000, v5
	v_add_f32_e32 v5, 0x358637bd, v5
	v_rsq_f32_e32 v6, v5
	s_nop 0
	s_add_u32 s98, s97, 9
	v_pk_mul_f32 v[64:65], v[64:65], v[6:7] op_sel_hi:[1,0]
	v_pk_mul_f32 v[66:67], v[66:67], v[6:7] op_sel_hi:[1,0]
	v_pk_mul_f32 v[68:69], v[68:69], v[6:7] op_sel_hi:[1,0]
	v_pk_mul_f32 v[70:71], v[70:71], v[6:7] op_sel_hi:[1,0]
	v_pk_mul_f32 v[72:73], v[72:73], v[6:7] op_sel_hi:[1,0]
	v_pk_mul_f32 v[74:75], v[74:75], v[6:7] op_sel_hi:[1,0]
	v_pk_mul_f32 v[76:77], v[76:77], v[6:7] op_sel_hi:[1,0]
	v_pk_mul_f32 v[78:79], v[78:79], v[6:7] op_sel_hi:[1,0]
	v_pk_mul_f32 v[64:65], v[64:65], v[112:113]
	v_pk_mul_f32 v[66:67], v[66:67], v[114:115]
	v_pk_mul_f32 v[68:69], v[68:69], v[116:117]
	v_pk_mul_f32 v[70:71], v[70:71], v[118:119]
	v_pk_mul_f32 v[72:73], v[72:73], v[120:121]
	v_pk_mul_f32 v[74:75], v[74:75], v[122:123]
	v_pk_mul_f32 v[76:77], v[76:77], v[124:125]
	v_pk_mul_f32 v[78:79], v[78:79], v[126:127]
	v_pk_fma_f32 v[64:65], v[64:65], v[128:129], v[144:145]
	v_pk_fma_f32 v[66:67], v[66:67], v[130:131], v[146:147]
	v_pk_fma_f32 v[68:69], v[68:69], v[132:133], v[148:149]
	v_pk_fma_f32 v[70:71], v[70:71], v[134:135], v[150:151]
	v_pk_fma_f32 v[72:73], v[72:73], v[136:137], v[152:153]
	v_pk_fma_f32 v[74:75], v[74:75], v[138:139], v[154:155]
	v_pk_fma_f32 v[76:77], v[76:77], v[140:141], v[156:157]
	v_pk_fma_f32 v[78:79], v[78:79], v[142:143], v[158:159]
	v_cvt_pk_bf16_f32 v64, v64, v65
	v_cvt_pk_bf16_f32 v65, v66, v67
	v_cvt_pk_bf16_f32 v66, v68, v69
	v_cvt_pk_bf16_f32 v67, v70, v71
	v_cvt_pk_bf16_f32 v68, v72, v73
	v_cvt_pk_bf16_f32 v69, v74, v75
	v_cvt_pk_bf16_f32 v70, v76, v77
	v_cvt_pk_bf16_f32 v71, v78, v79
	s_lshl_b32 s99, s98, 11
	v_lshl_add_u32 v8, v0, 3, s99
	global_store_dwordx2 v8, v[64:65], s[94:95]
	global_store_dwordx2 v8, v[66:67], s[94:95] offset:512
	global_store_dwordx2 v8, v[68:69], s[94:95] offset:1024
	global_store_dwordx2 v8, v[70:71], s[94:95] offset:1536
	s_lshl_b32 s99, s98, 2
	v_mov_b32_e32 v9, s99
	v_mov_b32_e32 v10, 0
	v_cmp_eq_u32_e32 vcc, 0, v0
	s_and_saveexec_b64 s[98:99], vcc
	global_store_dword v9, v10, s[90:91]
	global_store_dword v9, v10, s[92:93]
	s_or_b64 exec, exec, s[98:99]
	s_add_u32 s98, s97, 15
	s_lshl_b32 s98, s98, 12
	v_add_u32_e32 v3, s98, v1
	global_load_dwordx4 v[64:67], v3, s[88:89] nt
	global_load_dwordx4 v[68:71], v3, s[88:89] offset:1024 nt
	global_load_dwordx4 v[72:75], v3, s[88:89] offset:2048 nt
	global_load_dwordx4 v[76:79], v3, s[88:89] offset:3072 nt
	s_waitcnt vmcnt(50)
	v_mul_f32_e32 v4, v80, v80
	v_fma_f32 v4, v81, v81, v4
	v_fma_f32 v4, v82, v82, v4
	v_fma_f32 v4, v83, v83, v4
	v_fma_f32 v4, v84, v84, v4
	v_fma_f32 v4, v85, v85, v4
	v_fma_f32 v4, v86, v86, v4
	v_fma_f32 v4, v87, v87, v4
	v_fma_f32 v4, v88, v88, v4
	v_fma_f32 v4, v89, v89, v4
	v_fma_f32 v4, v90, v90, v4
	v_fma_f32 v4, v91, v91, v4
	v_fma_f32 v4, v92, v92, v4
	v_fma_f32 v4, v93, v93, v4
	v_fma_f32 v4, v94, v94, v4
	v_fma_f32 v4, v95, v95, v4
	s_nop 1
	v_add_f32_dpp v5, v4, v4 quad_perm:[1,0,3,2] row_mask:0xf bank_mask:0xf
	s_nop 1
	v_add_f32_dpp v4, v5, v5 quad_perm:[2,3,0,1] row_mask:0xf bank_mask:0xf
	s_nop 1
	v_add_f32_dpp v5, v4, v4 row_half_mirror row_mask:0xf bank_mask:0xf
	s_nop 1
	v_add_f32_dpp v4, v5, v5 row_mirror row_mask:0xf bank_mask:0xf
	s_nop 1
	v_readlane_b32 s98, v4, 0
	v_readlane_b32 s99, v4, 16
	s_nop 3
	v_mov_b32_e32 v5, s98
	v_add_f32_e32 v5, s99, v5
	v_readlane_b32 s98, v4, 32
	v_readlane_b32 s99, v4, 48
	s_nop 3
	v_add_f32_e32 v5, s98, v5
	v_add_f32_e32 v5, s99, v5
	v_mul_f32_e32 v5, 0x3a800000, v5
	v_add_f32_e32 v5, 0x358637bd, v5
	v_rsq_f32_e32 v6, v5
	s_nop 0
	s_add_u32 s98, s97, 10
	v_pk_mul_f32 v[80:81], v[80:81], v[6:7] op_sel_hi:[1,0]
	v_pk_mul_f32 v[82:83], v[82:83], v[6:7] op_sel_hi:[1,0]
	v_pk_mul_f32 v[84:85], v[84:85], v[6:7] op_sel_hi:[1,0]
	v_pk_mul_f32 v[86:87], v[86:87], v[6:7] op_sel_hi:[1,0]
	v_pk_mul_f32 v[88:89], v[88:89], v[6:7] op_sel_hi:[1,0]
	v_pk_mul_f32 v[90:91], v[90:91], v[6:7] op_sel_hi:[1,0]
	v_pk_mul_f32 v[92:93], v[92:93], v[6:7] op_sel_hi:[1,0]
	v_pk_mul_f32 v[94:95], v[94:95], v[6:7] op_sel_hi:[1,0]
	v_pk_mul_f32 v[80:81], v[80:81], v[112:113]
	v_pk_mul_f32 v[82:83], v[82:83], v[114:115]
	v_pk_mul_f32 v[84:85], v[84:85], v[116:117]
	v_pk_mul_f32 v[86:87], v[86:87], v[118:119]
	v_pk_mul_f32 v[88:89], v[88:89], v[120:121]
	v_pk_mul_f32 v[90:91], v[90:91], v[122:123]
	v_pk_mul_f32 v[92:93], v[92:93], v[124:125]
	v_pk_mul_f32 v[94:95], v[94:95], v[126:127]
	v_pk_fma_f32 v[80:81], v[80:81], v[128:129], v[144:145]
	v_pk_fma_f32 v[82:83], v[82:83], v[130:131], v[146:147]
	v_pk_fma_f32 v[84:85], v[84:85], v[132:133], v[148:149]
	v_pk_fma_f32 v[86:87], v[86:87], v[134:135], v[150:151]
	v_pk_fma_f32 v[88:89], v[88:89], v[136:137], v[152:153]
	v_pk_fma_f32 v[90:91], v[90:91], v[138:139], v[154:155]
	v_pk_fma_f32 v[92:93], v[92:93], v[140:141], v[156:157]
	v_pk_fma_f32 v[94:95], v[94:95], v[142:143], v[158:159]
	v_cvt_pk_bf16_f32 v80, v80, v81
	v_cvt_pk_bf16_f32 v81, v82, v83
	v_cvt_pk_bf16_f32 v82, v84, v85
	v_cvt_pk_bf16_f32 v83, v86, v87
	v_cvt_pk_bf16_f32 v84, v88, v89
	v_cvt_pk_bf16_f32 v85, v90, v91
	v_cvt_pk_bf16_f32 v86, v92, v93
	v_cvt_pk_bf16_f32 v87, v94, v95
	s_lshl_b32 s99, s98, 11
	v_lshl_add_u32 v8, v0, 3, s99
	global_store_dwordx2 v8, v[80:81], s[94:95]
	global_store_dwordx2 v8, v[82:83], s[94:95] offset:512
	global_store_dwordx2 v8, v[84:85], s[94:95] offset:1024
	global_store_dwordx2 v8, v[86:87], s[94:95] offset:1536
	s_lshl_b32 s99, s98, 2
	v_mov_b32_e32 v9, s99
	v_mov_b32_e32 v10, 0
	v_cmp_eq_u32_e32 vcc, 0, v0
	s_and_saveexec_b64 s[98:99], vcc
	global_store_dword v9, v10, s[90:91]
	global_store_dword v9, v10, s[92:93]
	s_or_b64 exec, exec, s[98:99]
	s_waitcnt vmcnt(46)
	v_mul_f32_e32 v4, v96, v96
	v_fma_f32 v4, v97, v97, v4
	v_fma_f32 v4, v98, v98, v4
	v_fma_f32 v4, v99, v99, v4
	v_fma_f32 v4, v100, v100, v4
	v_fma_f32 v4, v101, v101, v4
	v_fma_f32 v4, v102, v102, v4
	v_fma_f32 v4, v103, v103, v4
	v_fma_f32 v4, v104, v104, v4
	v_fma_f32 v4, v105, v105, v4
	v_fma_f32 v4, v106, v106, v4
	v_fma_f32 v4, v107, v107, v4
	v_fma_f32 v4, v108, v108, v4
	v_fma_f32 v4, v109, v109, v4
	v_fma_f32 v4, v110, v110, v4
	v_fma_f32 v4, v111, v111, v4
	s_nop 1
	v_add_f32_dpp v5, v4, v4 quad_perm:[1,0,3,2] row_mask:0xf bank_mask:0xf
	s_nop 1
	v_add_f32_dpp v4, v5, v5 quad_perm:[2,3,0,1] row_mask:0xf bank_mask:0xf
	s_nop 1
	v_add_f32_dpp v5, v4, v4 row_half_mirror row_mask:0xf bank_mask:0xf
	s_nop 1
	v_add_f32_dpp v4, v5, v5 row_mirror row_mask:0xf bank_mask:0xf
	s_nop 1
	v_readlane_b32 s98, v4, 0
	v_readlane_b32 s99, v4, 16
	s_nop 3
	v_mov_b32_e32 v5, s98
	v_add_f32_e32 v5, s99, v5
	v_readlane_b32 s98, v4, 32
	v_readlane_b32 s99, v4, 48
	s_nop 3
	v_add_f32_e32 v5, s98, v5
	v_add_f32_e32 v5, s99, v5
	v_mul_f32_e32 v5, 0x3a800000, v5
	v_add_f32_e32 v5, 0x358637bd, v5
	v_rsq_f32_e32 v6, v5
	s_nop 0
	s_add_u32 s98, s97, 11
	v_pk_mul_f32 v[96:97], v[96:97], v[6:7] op_sel_hi:[1,0]
	v_pk_mul_f32 v[98:99], v[98:99], v[6:7] op_sel_hi:[1,0]
	v_pk_mul_f32 v[100:101], v[100:101], v[6:7] op_sel_hi:[1,0]
	v_pk_mul_f32 v[102:103], v[102:103], v[6:7] op_sel_hi:[1,0]
	v_pk_mul_f32 v[104:105], v[104:105], v[6:7] op_sel_hi:[1,0]
	v_pk_mul_f32 v[106:107], v[106:107], v[6:7] op_sel_hi:[1,0]
	v_pk_mul_f32 v[108:109], v[108:109], v[6:7] op_sel_hi:[1,0]
	v_pk_mul_f32 v[110:111], v[110:111], v[6:7] op_sel_hi:[1,0]
	v_pk_mul_f32 v[96:97], v[96:97], v[112:113]
	v_pk_mul_f32 v[98:99], v[98:99], v[114:115]
	v_pk_mul_f32 v[100:101], v[100:101], v[116:117]
	v_pk_mul_f32 v[102:103], v[102:103], v[118:119]
	v_pk_mul_f32 v[104:105], v[104:105], v[120:121]
	v_pk_mul_f32 v[106:107], v[106:107], v[122:123]
	v_pk_mul_f32 v[108:109], v[108:109], v[124:125]
	v_pk_mul_f32 v[110:111], v[110:111], v[126:127]
	v_pk_fma_f32 v[96:97], v[96:97], v[128:129], v[144:145]
	v_pk_fma_f32 v[98:99], v[98:99], v[130:131], v[146:147]
	v_pk_fma_f32 v[100:101], v[100:101], v[132:133], v[148:149]
	v_pk_fma_f32 v[102:103], v[102:103], v[134:135], v[150:151]
	v_pk_fma_f32 v[104:105], v[104:105], v[136:137], v[152:153]
	v_pk_fma_f32 v[106:107], v[106:107], v[138:139], v[154:155]
	v_pk_fma_f32 v[108:109], v[108:109], v[140:141], v[156:157]
	v_pk_fma_f32 v[110:111], v[110:111], v[142:143], v[158:159]
	v_cvt_pk_bf16_f32 v96, v96, v97
	v_cvt_pk_bf16_f32 v97, v98, v99
	v_cvt_pk_bf16_f32 v98, v100, v101
	v_cvt_pk_bf16_f32 v99, v102, v103
	v_cvt_pk_bf16_f32 v100, v104, v105
	v_cvt_pk_bf16_f32 v101, v106, v107
	v_cvt_pk_bf16_f32 v102, v108, v109
	v_cvt_pk_bf16_f32 v103, v110, v111
	s_lshl_b32 s99, s98, 11
	v_lshl_add_u32 v8, v0, 3, s99
	global_store_dwordx2 v8, v[96:97], s[94:95]
	global_store_dwordx2 v8, v[98:99], s[94:95] offset:512
	global_store_dwordx2 v8, v[100:101], s[94:95] offset:1024
	global_store_dwordx2 v8, v[102:103], s[94:95] offset:1536
	s_lshl_b32 s99, s98, 2
	v_mov_b32_e32 v9, s99
	v_mov_b32_e32 v10, 0
	v_cmp_eq_u32_e32 vcc, 0, v0
	s_and_saveexec_b64 s[98:99], vcc
	global_store_dword v9, v10, s[90:91]
	global_store_dword v9, v10, s[92:93]
	s_or_b64 exec, exec, s[98:99]
	s_waitcnt vmcnt(42)
	v_mul_f32_e32 v4, v16, v16
	v_fma_f32 v4, v17, v17, v4
	v_fma_f32 v4, v18, v18, v4
	v_fma_f32 v4, v19, v19, v4
	v_fma_f32 v4, v20, v20, v4
	v_fma_f32 v4, v21, v21, v4
	v_fma_f32 v4, v22, v22, v4
	v_fma_f32 v4, v23, v23, v4
	v_fma_f32 v4, v24, v24, v4
	v_fma_f32 v4, v25, v25, v4
	v_fma_f32 v4, v26, v26, v4
	v_fma_f32 v4, v27, v27, v4
	v_fma_f32 v4, v28, v28, v4
	v_fma_f32 v4, v29, v29, v4
	v_fma_f32 v4, v30, v30, v4
	v_fma_f32 v4, v31, v31, v4
	s_nop 1
	v_add_f32_dpp v5, v4, v4 quad_perm:[1,0,3,2] row_mask:0xf bank_mask:0xf
	s_nop 1
	v_add_f32_dpp v4, v5, v5 quad_perm:[2,3,0,1] row_mask:0xf bank_mask:0xf
	s_nop 1
	v_add_f32_dpp v5, v4, v4 row_half_mirror row_mask:0xf bank_mask:0xf
	s_nop 1
	v_add_f32_dpp v4, v5, v5 row_mirror row_mask:0xf bank_mask:0xf
	s_nop 1
	v_readlane_b32 s98, v4, 0
	v_readlane_b32 s99, v4, 16
	s_nop 3
	v_mov_b32_e32 v5, s98
	v_add_f32_e32 v5, s99, v5
	v_readlane_b32 s98, v4, 32
	v_readlane_b32 s99, v4, 48
	s_nop 3
	v_add_f32_e32 v5, s98, v5
	v_add_f32_e32 v5, s99, v5
	v_mul_f32_e32 v5, 0x3a800000, v5
	v_add_f32_e32 v5, 0x358637bd, v5
	v_rsq_f32_e32 v6, v5
	s_nop 0
	s_add_u32 s98, s97, 12
	v_pk_mul_f32 v[16:17], v[16:17], v[6:7] op_sel_hi:[1,0]
	v_pk_mul_f32 v[18:19], v[18:19], v[6:7] op_sel_hi:[1,0]
	v_pk_mul_f32 v[20:21], v[20:21], v[6:7] op_sel_hi:[1,0]
	v_pk_mul_f32 v[22:23], v[22:23], v[6:7] op_sel_hi:[1,0]
	v_pk_mul_f32 v[24:25], v[24:25], v[6:7] op_sel_hi:[1,0]
	v_pk_mul_f32 v[26:27], v[26:27], v[6:7] op_sel_hi:[1,0]
	v_pk_mul_f32 v[28:29], v[28:29], v[6:7] op_sel_hi:[1,0]
	v_pk_mul_f32 v[30:31], v[30:31], v[6:7] op_sel_hi:[1,0]
	v_pk_mul_f32 v[16:17], v[16:17], v[112:113]
	v_pk_mul_f32 v[18:19], v[18:19], v[114:115]
	v_pk_mul_f32 v[20:21], v[20:21], v[116:117]
	v_pk_mul_f32 v[22:23], v[22:23], v[118:119]
	v_pk_mul_f32 v[24:25], v[24:25], v[120:121]
	v_pk_mul_f32 v[26:27], v[26:27], v[122:123]
	v_pk_mul_f32 v[28:29], v[28:29], v[124:125]
	v_pk_mul_f32 v[30:31], v[30:31], v[126:127]
	v_pk_fma_f32 v[16:17], v[16:17], v[128:129], v[144:145]
	v_pk_fma_f32 v[18:19], v[18:19], v[130:131], v[146:147]
	v_pk_fma_f32 v[20:21], v[20:21], v[132:133], v[148:149]
	v_pk_fma_f32 v[22:23], v[22:23], v[134:135], v[150:151]
	v_pk_fma_f32 v[24:25], v[24:25], v[136:137], v[152:153]
	v_pk_fma_f32 v[26:27], v[26:27], v[138:139], v[154:155]
	v_pk_fma_f32 v[28:29], v[28:29], v[140:141], v[156:157]
	v_pk_fma_f32 v[30:31], v[30:31], v[142:143], v[158:159]
	v_cvt_pk_bf16_f32 v16, v16, v17
	v_cvt_pk_bf16_f32 v17, v18, v19
	v_cvt_pk_bf16_f32 v18, v20, v21
	v_cvt_pk_bf16_f32 v19, v22, v23
	v_cvt_pk_bf16_f32 v20, v24, v25
	v_cvt_pk_bf16_f32 v21, v26, v27
	v_cvt_pk_bf16_f32 v22, v28, v29
	v_cvt_pk_bf16_f32 v23, v30, v31
	s_lshl_b32 s99, s98, 11
	v_lshl_add_u32 v8, v0, 3, s99
	global_store_dwordx2 v8, v[16:17], s[94:95]
	global_store_dwordx2 v8, v[18:19], s[94:95] offset:512
	global_store_dwordx2 v8, v[20:21], s[94:95] offset:1024
	global_store_dwordx2 v8, v[22:23], s[94:95] offset:1536
	s_lshl_b32 s99, s98, 2
	v_mov_b32_e32 v9, s99
	v_mov_b32_e32 v10, 0
	v_cmp_eq_u32_e32 vcc, 0, v0
	s_and_saveexec_b64 s[98:99], vcc
	global_store_dword v9, v10, s[90:91]
	global_store_dword v9, v10, s[92:93]
	s_or_b64 exec, exec, s[98:99]
	s_waitcnt vmcnt(38)
	v_mul_f32_e32 v4, v32, v32
	v_fma_f32 v4, v33, v33, v4
	v_fma_f32 v4, v34, v34, v4
	v_fma_f32 v4, v35, v35, v4
	v_fma_f32 v4, v36, v36, v4
	v_fma_f32 v4, v37, v37, v4
	v_fma_f32 v4, v38, v38, v4
	v_fma_f32 v4, v39, v39, v4
	v_fma_f32 v4, v40, v40, v4
	v_fma_f32 v4, v41, v41, v4
	v_fma_f32 v4, v42, v42, v4
	v_fma_f32 v4, v43, v43, v4
	v_fma_f32 v4, v44, v44, v4
	v_fma_f32 v4, v45, v45, v4
	v_fma_f32 v4, v46, v46, v4
	v_fma_f32 v4, v47, v47, v4
	s_nop 1
	v_add_f32_dpp v5, v4, v4 quad_perm:[1,0,3,2] row_mask:0xf bank_mask:0xf
	s_nop 1
	v_add_f32_dpp v4, v5, v5 quad_perm:[2,3,0,1] row_mask:0xf bank_mask:0xf
	s_nop 1
	v_add_f32_dpp v5, v4, v4 row_half_mirror row_mask:0xf bank_mask:0xf
	s_nop 1
	v_add_f32_dpp v4, v5, v5 row_mirror row_mask:0xf bank_mask:0xf
	s_nop 1
	v_readlane_b32 s98, v4, 0
	v_readlane_b32 s99, v4, 16
	s_nop 3
	v_mov_b32_e32 v5, s98
	v_add_f32_e32 v5, s99, v5
	v_readlane_b32 s98, v4, 32
	v_readlane_b32 s99, v4, 48
	s_nop 3
	v_add_f32_e32 v5, s98, v5
	v_add_f32_e32 v5, s99, v5
	v_mul_f32_e32 v5, 0x3a800000, v5
	v_add_f32_e32 v5, 0x358637bd, v5
	v_rsq_f32_e32 v6, v5
	s_nop 0
	s_add_u32 s98, s97, 13
	v_pk_mul_f32 v[32:33], v[32:33], v[6:7] op_sel_hi:[1,0]
	v_pk_mul_f32 v[34:35], v[34:35], v[6:7] op_sel_hi:[1,0]
	v_pk_mul_f32 v[36:37], v[36:37], v[6:7] op_sel_hi:[1,0]
	v_pk_mul_f32 v[38:39], v[38:39], v[6:7] op_sel_hi:[1,0]
	v_pk_mul_f32 v[40:41], v[40:41], v[6:7] op_sel_hi:[1,0]
	v_pk_mul_f32 v[42:43], v[42:43], v[6:7] op_sel_hi:[1,0]
	v_pk_mul_f32 v[44:45], v[44:45], v[6:7] op_sel_hi:[1,0]
	v_pk_mul_f32 v[46:47], v[46:47], v[6:7] op_sel_hi:[1,0]
	v_pk_mul_f32 v[32:33], v[32:33], v[112:113]
	v_pk_mul_f32 v[34:35], v[34:35], v[114:115]
	v_pk_mul_f32 v[36:37], v[36:37], v[116:117]
	v_pk_mul_f32 v[38:39], v[38:39], v[118:119]
	v_pk_mul_f32 v[40:41], v[40:41], v[120:121]
	v_pk_mul_f32 v[42:43], v[42:43], v[122:123]
	v_pk_mul_f32 v[44:45], v[44:45], v[124:125]
	v_pk_mul_f32 v[46:47], v[46:47], v[126:127]
	v_pk_fma_f32 v[32:33], v[32:33], v[128:129], v[144:145]
	v_pk_fma_f32 v[34:35], v[34:35], v[130:131], v[146:147]
	v_pk_fma_f32 v[36:37], v[36:37], v[132:133], v[148:149]
	v_pk_fma_f32 v[38:39], v[38:39], v[134:135], v[150:151]
	v_pk_fma_f32 v[40:41], v[40:41], v[136:137], v[152:153]
	v_pk_fma_f32 v[42:43], v[42:43], v[138:139], v[154:155]
	v_pk_fma_f32 v[44:45], v[44:45], v[140:141], v[156:157]
	v_pk_fma_f32 v[46:47], v[46:47], v[142:143], v[158:159]
	v_cvt_pk_bf16_f32 v32, v32, v33
	v_cvt_pk_bf16_f32 v33, v34, v35
	v_cvt_pk_bf16_f32 v34, v36, v37
	v_cvt_pk_bf16_f32 v35, v38, v39
	v_cvt_pk_bf16_f32 v36, v40, v41
	v_cvt_pk_bf16_f32 v37, v42, v43
	v_cvt_pk_bf16_f32 v38, v44, v45
	v_cvt_pk_bf16_f32 v39, v46, v47
	s_lshl_b32 s99, s98, 11
	v_lshl_add_u32 v8, v0, 3, s99
	global_store_dwordx2 v8, v[32:33], s[94:95]
	global_store_dwordx2 v8, v[34:35], s[94:95] offset:512
	global_store_dwordx2 v8, v[36:37], s[94:95] offset:1024
	global_store_dwordx2 v8, v[38:39], s[94:95] offset:1536
	s_lshl_b32 s99, s98, 2
	v_mov_b32_e32 v9, s99
	v_mov_b32_e32 v10, 0
	v_cmp_eq_u32_e32 vcc, 0, v0
	s_and_saveexec_b64 s[98:99], vcc
	global_store_dword v9, v10, s[90:91]
	global_store_dword v9, v10, s[92:93]
	s_or_b64 exec, exec, s[98:99]
	s_waitcnt vmcnt(34)
	v_mul_f32_e32 v4, v48, v48
	v_fma_f32 v4, v49, v49, v4
	v_fma_f32 v4, v50, v50, v4
	v_fma_f32 v4, v51, v51, v4
	v_fma_f32 v4, v52, v52, v4
	v_fma_f32 v4, v53, v53, v4
	v_fma_f32 v4, v54, v54, v4
	v_fma_f32 v4, v55, v55, v4
	v_fma_f32 v4, v56, v56, v4
	v_fma_f32 v4, v57, v57, v4
	v_fma_f32 v4, v58, v58, v4
	v_fma_f32 v4, v59, v59, v4
	v_fma_f32 v4, v60, v60, v4
	v_fma_f32 v4, v61, v61, v4
	v_fma_f32 v4, v62, v62, v4
	v_fma_f32 v4, v63, v63, v4
	s_nop 1
	v_add_f32_dpp v5, v4, v4 quad_perm:[1,0,3,2] row_mask:0xf bank_mask:0xf
	s_nop 1
	v_add_f32_dpp v4, v5, v5 quad_perm:[2,3,0,1] row_mask:0xf bank_mask:0xf
	s_nop 1
	v_add_f32_dpp v5, v4, v4 row_half_mirror row_mask:0xf bank_mask:0xf
	s_nop 1
	v_add_f32_dpp v4, v5, v5 row_mirror row_mask:0xf bank_mask:0xf
	s_nop 1
	v_readlane_b32 s98, v4, 0
	v_readlane_b32 s99, v4, 16
	s_nop 3
	v_mov_b32_e32 v5, s98
	v_add_f32_e32 v5, s99, v5
	v_readlane_b32 s98, v4, 32
	v_readlane_b32 s99, v4, 48
	s_nop 3
	v_add_f32_e32 v5, s98, v5
	v_add_f32_e32 v5, s99, v5
	v_mul_f32_e32 v5, 0x3a800000, v5
	v_add_f32_e32 v5, 0x358637bd, v5
	v_rsq_f32_e32 v6, v5
	s_nop 0
	s_add_u32 s98, s97, 14
	v_pk_mul_f32 v[48:49], v[48:49], v[6:7] op_sel_hi:[1,0]
	v_pk_mul_f32 v[50:51], v[50:51], v[6:7] op_sel_hi:[1,0]
	v_pk_mul_f32 v[52:53], v[52:53], v[6:7] op_sel_hi:[1,0]
	v_pk_mul_f32 v[54:55], v[54:55], v[6:7] op_sel_hi:[1,0]
	v_pk_mul_f32 v[56:57], v[56:57], v[6:7] op_sel_hi:[1,0]
	v_pk_mul_f32 v[58:59], v[58:59], v[6:7] op_sel_hi:[1,0]
	v_pk_mul_f32 v[60:61], v[60:61], v[6:7] op_sel_hi:[1,0]
	v_pk_mul_f32 v[62:63], v[62:63], v[6:7] op_sel_hi:[1,0]
	v_pk_mul_f32 v[48:49], v[48:49], v[112:113]
	v_pk_mul_f32 v[50:51], v[50:51], v[114:115]
	v_pk_mul_f32 v[52:53], v[52:53], v[116:117]
	v_pk_mul_f32 v[54:55], v[54:55], v[118:119]
	v_pk_mul_f32 v[56:57], v[56:57], v[120:121]
	v_pk_mul_f32 v[58:59], v[58:59], v[122:123]
	v_pk_mul_f32 v[60:61], v[60:61], v[124:125]
	v_pk_mul_f32 v[62:63], v[62:63], v[126:127]
	v_pk_fma_f32 v[48:49], v[48:49], v[128:129], v[144:145]
	v_pk_fma_f32 v[50:51], v[50:51], v[130:131], v[146:147]
	v_pk_fma_f32 v[52:53], v[52:53], v[132:133], v[148:149]
	v_pk_fma_f32 v[54:55], v[54:55], v[134:135], v[150:151]
	v_pk_fma_f32 v[56:57], v[56:57], v[136:137], v[152:153]
	v_pk_fma_f32 v[58:59], v[58:59], v[138:139], v[154:155]
	v_pk_fma_f32 v[60:61], v[60:61], v[140:141], v[156:157]
	v_pk_fma_f32 v[62:63], v[62:63], v[142:143], v[158:159]
	v_cvt_pk_bf16_f32 v48, v48, v49
	v_cvt_pk_bf16_f32 v49, v50, v51
	v_cvt_pk_bf16_f32 v50, v52, v53
	v_cvt_pk_bf16_f32 v51, v54, v55
	v_cvt_pk_bf16_f32 v52, v56, v57
	v_cvt_pk_bf16_f32 v53, v58, v59
	v_cvt_pk_bf16_f32 v54, v60, v61
	v_cvt_pk_bf16_f32 v55, v62, v63
	s_lshl_b32 s99, s98, 11
	v_lshl_add_u32 v8, v0, 3, s99
	global_store_dwordx2 v8, v[48:49], s[94:95]
	global_store_dwordx2 v8, v[50:51], s[94:95] offset:512
	global_store_dwordx2 v8, v[52:53], s[94:95] offset:1024
	global_store_dwordx2 v8, v[54:55], s[94:95] offset:1536
	s_lshl_b32 s99, s98, 2
	v_mov_b32_e32 v9, s99
	v_mov_b32_e32 v10, 0
	v_cmp_eq_u32_e32 vcc, 0, v0
	s_and_saveexec_b64 s[98:99], vcc
	global_store_dword v9, v10, s[90:91]
	global_store_dword v9, v10, s[92:93]
	s_or_b64 exec, exec, s[98:99]
	s_waitcnt vmcnt(30)
	v_mul_f32_e32 v4, v64, v64
	v_fma_f32 v4, v65, v65, v4
	v_fma_f32 v4, v66, v66, v4
	v_fma_f32 v4, v67, v67, v4
	v_fma_f32 v4, v68, v68, v4
	v_fma_f32 v4, v69, v69, v4
	v_fma_f32 v4, v70, v70, v4
	v_fma_f32 v4, v71, v71, v4
	v_fma_f32 v4, v72, v72, v4
	v_fma_f32 v4, v73, v73, v4
	v_fma_f32 v4, v74, v74, v4
	v_fma_f32 v4, v75, v75, v4
	v_fma_f32 v4, v76, v76, v4
	v_fma_f32 v4, v77, v77, v4
	v_fma_f32 v4, v78, v78, v4
	v_fma_f32 v4, v79, v79, v4
	s_nop 1
	v_add_f32_dpp v5, v4, v4 quad_perm:[1,0,3,2] row_mask:0xf bank_mask:0xf
	s_nop 1
	v_add_f32_dpp v4, v5, v5 quad_perm:[2,3,0,1] row_mask:0xf bank_mask:0xf
	s_nop 1
	v_add_f32_dpp v5, v4, v4 row_half_mirror row_mask:0xf bank_mask:0xf
	s_nop 1
	v_add_f32_dpp v4, v5, v5 row_mirror row_mask:0xf bank_mask:0xf
	s_nop 1
	v_readlane_b32 s98, v4, 0
	v_readlane_b32 s99, v4, 16
	s_nop 3
	v_mov_b32_e32 v5, s98
	v_add_f32_e32 v5, s99, v5
	v_readlane_b32 s98, v4, 32
	v_readlane_b32 s99, v4, 48
	s_nop 3
	v_add_f32_e32 v5, s98, v5
	v_add_f32_e32 v5, s99, v5
	v_mul_f32_e32 v5, 0x3a800000, v5
	v_add_f32_e32 v5, 0x358637bd, v5
	v_rsq_f32_e32 v6, v5
	s_nop 0
	s_add_u32 s98, s97, 15
	v_pk_mul_f32 v[64:65], v[64:65], v[6:7] op_sel_hi:[1,0]
	v_pk_mul_f32 v[66:67], v[66:67], v[6:7] op_sel_hi:[1,0]
	v_pk_mul_f32 v[68:69], v[68:69], v[6:7] op_sel_hi:[1,0]
	v_pk_mul_f32 v[70:71], v[70:71], v[6:7] op_sel_hi:[1,0]
	v_pk_mul_f32 v[72:73], v[72:73], v[6:7] op_sel_hi:[1,0]
	v_pk_mul_f32 v[74:75], v[74:75], v[6:7] op_sel_hi:[1,0]
	v_pk_mul_f32 v[76:77], v[76:77], v[6:7] op_sel_hi:[1,0]
	v_pk_mul_f32 v[78:79], v[78:79], v[6:7] op_sel_hi:[1,0]
	v_pk_mul_f32 v[64:65], v[64:65], v[112:113]
	v_pk_mul_f32 v[66:67], v[66:67], v[114:115]
	v_pk_mul_f32 v[68:69], v[68:69], v[116:117]
	v_pk_mul_f32 v[70:71], v[70:71], v[118:119]
	v_pk_mul_f32 v[72:73], v[72:73], v[120:121]
	v_pk_mul_f32 v[74:75], v[74:75], v[122:123]
	v_pk_mul_f32 v[76:77], v[76:77], v[124:125]
	v_pk_mul_f32 v[78:79], v[78:79], v[126:127]
	v_pk_fma_f32 v[64:65], v[64:65], v[128:129], v[144:145]
	v_pk_fma_f32 v[66:67], v[66:67], v[130:131], v[146:147]
	v_pk_fma_f32 v[68:69], v[68:69], v[132:133], v[148:149]
	v_pk_fma_f32 v[70:71], v[70:71], v[134:135], v[150:151]
	v_pk_fma_f32 v[72:73], v[72:73], v[136:137], v[152:153]
	v_pk_fma_f32 v[74:75], v[74:75], v[138:139], v[154:155]
	v_pk_fma_f32 v[76:77], v[76:77], v[140:141], v[156:157]
	v_pk_fma_f32 v[78:79], v[78:79], v[142:143], v[158:159]
	v_cvt_pk_bf16_f32 v64, v64, v65
	v_cvt_pk_bf16_f32 v65, v66, v67
	v_cvt_pk_bf16_f32 v66, v68, v69
	v_cvt_pk_bf16_f32 v67, v70, v71
	v_cvt_pk_bf16_f32 v68, v72, v73
	v_cvt_pk_bf16_f32 v69, v74, v75
	v_cvt_pk_bf16_f32 v70, v76, v77
	v_cvt_pk_bf16_f32 v71, v78, v79
	s_lshl_b32 s99, s98, 11
	v_lshl_add_u32 v8, v0, 3, s99
	global_store_dwordx2 v8, v[64:65], s[94:95]
	global_store_dwordx2 v8, v[66:67], s[94:95] offset:512
	global_store_dwordx2 v8, v[68:69], s[94:95] offset:1024
	global_store_dwordx2 v8, v[70:71], s[94:95] offset:1536
	s_lshl_b32 s99, s98, 2
	v_mov_b32_e32 v9, s99
	v_mov_b32_e32 v10, 0
	v_cmp_eq_u32_e32 vcc, 0, v0
	s_and_saveexec_b64 s[98:99], vcc
	global_store_dword v9, v10, s[90:91]
	global_store_dword v9, v10, s[92:93]
	s_or_b64 exec, exec, s[98:99]
	s_waitcnt vmcnt(0)
